# dense-attention phase: blocks without an S1 tile take the last light item of the blocks that have one
# baseline (speedup 1.0000x reference)
.LBB0_1249:
	s_cmpk_lg_i32 s89, 0x100
	s_cbranch_scc1 .Ls1_orig
	v_readlane_b32 s2, v255, 22
	s_cmpk_lt_i32 s2, 0xc0
	s_cbranch_scc0 .Ls1_high
	s_add_i32 s4, s4, 0x100
	s_cmpk_lt_i32 s4, 0x300
	s_cbranch_scc1 .LBB0_1250
	s_cmpk_gt_i32 s4, 0x3ff
	s_cbranch_scc1 .LBB0_1292
	s_add_i32 s4, s4, 0x100
	s_branch .LBB0_1250
.Ls1_high:
	s_cmpk_lt_i32 s4, 0x300
	s_cbranch_scc0 .Ls1_h2
	s_add_i32 s4, s4, 0x100
	s_branch .LBB0_1250
.Ls1_h2:
	s_cmpk_lt_i32 s4, 0x3c0
	s_cbranch_scc1 .Ls1_ext
	s_sub_i32 s2, s2, 0xc0
	s_mul_i32 s2, s2, 3
	s_add_i32 s4, s2, 0x300
	s_branch .LBB0_1250
.Ls1_ext:
	s_sub_i32 s3, s4, 0x300
	s_mul_hi_u32 s2, s3, 0xaaaaaaab
	s_lshr_b32 s2, s2, 1
	s_mul_i32 s2, s2, 3
	s_sub_i32 s3, s3, s2
	s_cmp_eq_u32 s3, 2
	s_cbranch_scc1 .LBB0_1292
	s_add_i32 s4, s4, 1
	s_branch .LBB0_1250
